# grid barrier: non-last workgroups poll the top-level generation word directly (per-XCD generation hop removed)
# speedup vs baseline: 1.0046x; 1.0046x over previous
.LBB0_87:
	s_or_b64 exec, exec, s[6:7]
	v_cvt_f32_u32_e32 v5, v3
	s_waitcnt vmcnt(0)
	v_readfirstlane_b32 s2, v4
	v_sub_u32_e32 v4, 0, v3
	v_rcp_iflag_f32_e32 v5, v5
	v_add_u32_e32 v6, s2, v2
	v_mul_f32_e32 v5, 0x4f7ffffe, v5
	v_cvt_u32_f32_e32 v5, v5
	v_mul_lo_u32 v2, v4, v5
	v_mul_hi_u32 v2, v5, v2
	v_add_u32_e32 v2, v5, v2
	v_mul_hi_u32 v2, v6, v2
	v_mul_lo_u32 v4, v2, v3
	v_sub_u32_e32 v4, v6, v4
	v_add_u32_e32 v5, 1, v2
	v_cmp_ge_u32_e32 vcc, v4, v3
	s_nop 1
	v_cndmask_b32_e32 v2, v2, v5, vcc
	v_sub_u32_e32 v5, v4, v3
	v_cndmask_b32_e32 v4, v4, v5, vcc
	v_add_u32_e32 v5, 1, v2
	v_cmp_ge_u32_e32 vcc, v4, v3
	v_add_u32_e32 v4, 1, v6
	s_nop 0
	v_cndmask_b32_e32 v2, v2, v5, vcc
	v_mul_lo_u32 v5, v3, v2
	v_add_u32_e32 v3, v5, v3
	v_cmp_ne_u32_e32 vcc, v4, v3
	s_and_saveexec_b64 s[2:3], vcc
	s_xor_b64 s[2:3], exec, s[2:3]
	s_cbranch_execz .LBB0_101
	s_movk_i32 s6, 0xd40
	s_mov_b32 s7, 0
	s_lshl_b64 s[6:7], s[6:7], 2
	s_add_u32 s8, s42, s6
	s_addc_u32 s9, s43, s7
	s_waitcnt lgkmcnt(0)
	v_mov_b32_e32 v1, 0
	global_load_dword v3, v1, s[8:9] sc1
	s_waitcnt vmcnt(0)
	v_cmp_eq_u32_e32 vcc, v3, v2
	s_and_saveexec_b64 s[6:7], vcc
	s_cbranch_execz .LBB0_100
	s_mov_b32 s20, 1
	s_mov_b64 s[10:11], 0
	s_branch .LBB0_91

.LBB0_118:
	s_or_b64 exec, exec, s[2:3]
	s_mov_b64 s[2:3], exec
	v_mbcnt_lo_u32_b32 v1, s2, 0
	v_mbcnt_hi_u32_b32 v1, s3, v1
	s_mov_b32 s9, 0
	v_cmp_eq_u32_e32 vcc, 0, v1
	s_waitcnt vmcnt(0)
	buffer_inv sc1
	s_and_saveexec_b64 s[6:7], vcc
	s_cbranch_execz .LBB0_120
	s_add_i32 s8, s22, 0x900
	s_lshl_b64 s[8:9], s[8:9], 2
	s_add_u32 s8, s42, s8
	s_addc_u32 s9, s43, s9
	s_bcnt1_i32_b64 s2, s[2:3]
	v_mov_b32_e32 v1, 0
	v_mov_b32_e32 v2, s2
.LBB0_120:
	s_or_b64 exec, exec, s[6:7]
	s_waitcnt vmcnt(0)

.LBB0_145:
	s_or_b64 exec, exec, s[6:7]
	v_cvt_f32_u32_e32 v5, v3
	s_waitcnt vmcnt(0)
	v_readfirstlane_b32 s4, v4
	v_sub_u32_e32 v4, 0, v3
	v_rcp_iflag_f32_e32 v5, v5
	v_add_u32_e32 v6, s4, v2
	v_mul_f32_e32 v5, 0x4f7ffffe, v5
	v_cvt_u32_f32_e32 v5, v5
	v_mul_lo_u32 v2, v4, v5
	v_mul_hi_u32 v2, v5, v2
	v_add_u32_e32 v2, v5, v2
	v_mul_hi_u32 v2, v6, v2
	v_mul_lo_u32 v4, v2, v3
	v_sub_u32_e32 v4, v6, v4
	v_add_u32_e32 v5, 1, v2
	v_cmp_ge_u32_e32 vcc, v4, v3
	s_nop 1
	v_cndmask_b32_e32 v2, v2, v5, vcc
	v_sub_u32_e32 v5, v4, v3
	v_cndmask_b32_e32 v4, v4, v5, vcc
	v_add_u32_e32 v5, 1, v2
	v_cmp_ge_u32_e32 vcc, v4, v3
	v_add_u32_e32 v4, 1, v6
	s_nop 0
	v_cndmask_b32_e32 v2, v2, v5, vcc
	v_mul_lo_u32 v5, v3, v2
	v_add_u32_e32 v3, v5, v3
	v_cmp_ne_u32_e32 vcc, v4, v3
	s_and_saveexec_b64 s[4:5], vcc
	s_xor_b64 s[4:5], exec, s[4:5]
	s_cbranch_execz .LBB0_159
	s_movk_i32 s6, 0xd40
	s_mov_b32 s7, 0
	s_lshl_b64 s[6:7], s[6:7], 2
	s_add_u32 s8, s42, s6
	s_addc_u32 s9, s43, s7
	s_waitcnt lgkmcnt(0)
	v_mov_b32_e32 v1, 0
	global_load_dword v3, v1, s[8:9] sc1
	s_waitcnt vmcnt(0)
	v_cmp_eq_u32_e32 vcc, v3, v2
	s_and_saveexec_b64 s[6:7], vcc
	s_cbranch_execz .LBB0_158
	s_mov_b32 s20, 1
	s_mov_b64 s[10:11], 0
	s_branch .LBB0_149

.LBB0_176:
	s_or_b64 exec, exec, s[4:5]
	s_mov_b64 s[4:5], exec
	v_mbcnt_lo_u32_b32 v1, s4, 0
	v_mbcnt_hi_u32_b32 v1, s5, v1
	s_mov_b32 s9, 0
	v_cmp_eq_u32_e32 vcc, 0, v1
	s_waitcnt vmcnt(0)
	buffer_inv sc1
	s_and_saveexec_b64 s[6:7], vcc
	s_cbranch_execz .LBB0_178
	s_add_i32 s8, s22, 0x900
	s_lshl_b64 s[8:9], s[8:9], 2
	s_add_u32 s8, s42, s8
	s_addc_u32 s9, s43, s9
	s_bcnt1_i32_b64 s4, s[4:5]
	v_mov_b32_e32 v1, 0
	v_mov_b32_e32 v2, s4
.LBB0_178:
	s_or_b64 exec, exec, s[6:7]
	s_waitcnt vmcnt(0)

.LBB0_306:
	s_or_b64 exec, exec, s[4:5]
	s_mov_b64 s[4:5], exec
	v_mbcnt_lo_u32_b32 v1, s4, 0
	v_mbcnt_hi_u32_b32 v1, s5, v1
	s_mov_b32 s9, 0
	v_cmp_eq_u32_e32 vcc, 0, v1
	s_waitcnt vmcnt(0)
	buffer_inv sc1
	s_and_saveexec_b64 s[6:7], vcc
	s_cbranch_execz .LBB0_308
	s_add_i32 s8, s22, 0x900
	s_lshl_b64 s[8:9], s[8:9], 2
	s_add_u32 s8, s42, s8
	s_addc_u32 s9, s43, s9
	s_bcnt1_i32_b64 s4, s[4:5]
	v_mov_b32_e32 v1, 0
	v_mov_b32_e32 v2, s4
.LBB0_308:
	s_or_b64 exec, exec, s[6:7]
	s_waitcnt vmcnt(0)

.LBB0_400:
	s_or_b64 exec, exec, s[4:5]
	s_mov_b64 s[4:5], exec
	v_mbcnt_lo_u32_b32 v1, s4, 0
	v_mbcnt_hi_u32_b32 v1, s5, v1
	s_mov_b32 s9, 0
	v_cmp_eq_u32_e32 vcc, 0, v1
	s_waitcnt vmcnt(0)
	buffer_inv sc1
	s_and_saveexec_b64 s[6:7], vcc
	s_cbranch_execz .LBB0_402
	s_add_i32 s8, s22, 0x900
	s_lshl_b64 s[8:9], s[8:9], 2
	s_add_u32 s8, s42, s8
	s_addc_u32 s9, s43, s9
	s_bcnt1_i32_b64 s4, s[4:5]
	v_mov_b32_e32 v1, 0
	v_mov_b32_e32 v2, s4
.LBB0_402:
	s_or_b64 exec, exec, s[6:7]
	s_waitcnt vmcnt(0)

.LBB0_485:
	s_or_b64 exec, exec, s[4:5]
	s_mov_b64 s[4:5], exec
	v_mbcnt_lo_u32_b32 v1, s4, 0
	v_mbcnt_hi_u32_b32 v1, s5, v1
	s_mov_b32 s9, 0
	v_cmp_eq_u32_e32 vcc, 0, v1
	s_waitcnt vmcnt(0)
	buffer_inv sc1
	s_and_saveexec_b64 s[6:7], vcc
	s_cbranch_execz .LBB0_487
	s_add_i32 s8, s22, 0x900
	s_lshl_b64 s[8:9], s[8:9], 2
	s_add_u32 s8, s42, s8
	s_addc_u32 s9, s43, s9
	s_bcnt1_i32_b64 s4, s[4:5]
	v_mov_b32_e32 v1, 0
	v_mov_b32_e32 v2, s4
.LBB0_487:
	s_or_b64 exec, exec, s[6:7]
	s_waitcnt vmcnt(0)

.LBB0_543:
	s_or_b64 exec, exec, s[2:3]
	s_mov_b64 s[2:3], exec
	v_mbcnt_lo_u32_b32 v1, s2, 0
	v_mbcnt_hi_u32_b32 v1, s3, v1
	s_mov_b32 s9, 0
	v_cmp_eq_u32_e32 vcc, 0, v1
	s_waitcnt vmcnt(0)
	buffer_inv sc1
	s_and_saveexec_b64 s[6:7], vcc
	s_cbranch_execz .LBB0_545
	s_add_i32 s8, s22, 0x900
	s_lshl_b64 s[8:9], s[8:9], 2
	s_add_u32 s8, s42, s8
	s_addc_u32 s9, s43, s9
	s_bcnt1_i32_b64 s2, s[2:3]
	v_mov_b32_e32 v1, 0
	v_mov_b32_e32 v2, s2
.LBB0_545:
	s_or_b64 exec, exec, s[6:7]
	s_waitcnt vmcnt(0)

.LBB0_625:
	s_or_b64 exec, exec, s[2:3]
	s_mov_b64 s[2:3], exec
	v_mbcnt_lo_u32_b32 v1, s2, 0
	v_mbcnt_hi_u32_b32 v1, s3, v1
	s_mov_b32 s9, 0
	v_cmp_eq_u32_e32 vcc, 0, v1
	s_waitcnt vmcnt(0)
	buffer_inv sc1
	s_and_saveexec_b64 s[6:7], vcc
	s_cbranch_execz .LBB0_627
	s_add_i32 s8, s22, 0x900
	s_lshl_b64 s[8:9], s[8:9], 2
	s_add_u32 s8, s42, s8
	s_addc_u32 s9, s43, s9
	s_bcnt1_i32_b64 s2, s[2:3]
	v_mov_b32_e32 v1, 0
	v_mov_b32_e32 v2, s2
.LBB0_627:
	s_or_b64 exec, exec, s[6:7]
	s_waitcnt vmcnt(0)

.LBB0_717:
	s_or_b64 exec, exec, s[2:3]
	s_mov_b64 s[2:3], exec
	v_mbcnt_lo_u32_b32 v1, s2, 0
	v_mbcnt_hi_u32_b32 v1, s3, v1
	s_mov_b32 s9, 0
	v_cmp_eq_u32_e32 vcc, 0, v1
	s_waitcnt vmcnt(0)
	buffer_inv sc1
	s_and_saveexec_b64 s[6:7], vcc
	s_cbranch_execz .LBB0_719
	s_add_i32 s8, s22, 0x900
	s_lshl_b64 s[8:9], s[8:9], 2
	s_add_u32 s8, s42, s8
	s_addc_u32 s9, s43, s9
	s_bcnt1_i32_b64 s2, s[2:3]
	v_mov_b32_e32 v1, 0
	v_mov_b32_e32 v2, s2
.LBB0_719:
	s_or_b64 exec, exec, s[6:7]
	s_waitcnt vmcnt(0)

.LBB0_775:
	s_or_b64 exec, exec, s[4:5]
	s_mov_b64 s[4:5], exec
	v_mbcnt_lo_u32_b32 v1, s4, 0
	v_mbcnt_hi_u32_b32 v1, s5, v1
	s_mov_b32 s9, 0
	v_cmp_eq_u32_e32 vcc, 0, v1
	s_waitcnt vmcnt(0)
	buffer_inv sc1
	s_and_saveexec_b64 s[6:7], vcc
	s_cbranch_execz .LBB0_777
	s_add_i32 s8, s22, 0x900
	s_lshl_b64 s[8:9], s[8:9], 2
	s_add_u32 s8, s42, s8
	s_addc_u32 s9, s43, s9
	s_bcnt1_i32_b64 s4, s[4:5]
	v_mov_b32_e32 v1, 0
	v_mov_b32_e32 v2, s4
.LBB0_777:
	s_or_b64 exec, exec, s[6:7]
	s_waitcnt vmcnt(0)

.LBB0_825:
	s_or_b64 exec, exec, s[4:5]
	v_cvt_f32_u32_e32 v5, v3
	s_waitcnt vmcnt(0)
	v_readfirstlane_b32 s2, v4
	v_sub_u32_e32 v4, 0, v3
	v_rcp_iflag_f32_e32 v5, v5
	v_add_u32_e32 v6, s2, v2
	v_mul_f32_e32 v5, 0x4f7ffffe, v5
	v_cvt_u32_f32_e32 v5, v5
	v_mul_lo_u32 v2, v4, v5
	v_mul_hi_u32 v2, v5, v2
	v_add_u32_e32 v2, v5, v2
	v_mul_hi_u32 v2, v6, v2
	v_mul_lo_u32 v4, v2, v3
	v_sub_u32_e32 v4, v6, v4
	v_add_u32_e32 v5, 1, v2
	v_cmp_ge_u32_e32 vcc, v4, v3
	s_nop 1
	v_cndmask_b32_e32 v2, v2, v5, vcc
	v_sub_u32_e32 v5, v4, v3
	v_cndmask_b32_e32 v4, v4, v5, vcc
	v_add_u32_e32 v5, 1, v2
	v_cmp_ge_u32_e32 vcc, v4, v3
	v_add_u32_e32 v4, 1, v6
	s_nop 0
	v_cndmask_b32_e32 v2, v2, v5, vcc
	v_mul_lo_u32 v5, v3, v2
	v_add_u32_e32 v3, v5, v3
	v_cmp_ne_u32_e32 vcc, v4, v3
	s_and_saveexec_b64 s[2:3], vcc
	s_xor_b64 s[2:3], exec, s[2:3]
	s_cbranch_execz .LBB0_839
	s_movk_i32 s4, 0xd40
	s_mov_b32 s5, 0
	s_lshl_b64 s[4:5], s[4:5], 2
	s_add_u32 s8, s42, s4
	s_addc_u32 s9, s43, s5
	s_waitcnt lgkmcnt(0)
	v_mov_b32_e32 v1, 0
	global_load_dword v3, v1, s[8:9] sc1
	s_waitcnt vmcnt(0)
	v_cmp_eq_u32_e32 vcc, v3, v2
	s_and_saveexec_b64 s[4:5], vcc
	s_cbranch_execz .LBB0_838
	s_mov_b32 s20, 1
	s_mov_b64 s[10:11], 0
	s_branch .LBB0_829

.LBB0_856:
	s_or_b64 exec, exec, s[2:3]
	s_mov_b64 s[2:3], exec
	v_mbcnt_lo_u32_b32 v1, s2, 0
	v_mbcnt_hi_u32_b32 v1, s3, v1
	s_mov_b32 s9, 0
	v_cmp_eq_u32_e32 vcc, 0, v1
	s_waitcnt vmcnt(0)
	buffer_inv sc1
	s_and_saveexec_b64 s[4:5], vcc
	s_cbranch_execz .LBB0_858
	s_add_i32 s8, s22, 0x900
	s_lshl_b64 s[8:9], s[8:9], 2
	s_add_u32 s8, s42, s8
	s_addc_u32 s9, s43, s9
	s_bcnt1_i32_b64 s2, s[2:3]
	v_mov_b32_e32 v1, 0
	v_mov_b32_e32 v2, s2
.LBB0_858:
	s_or_b64 exec, exec, s[4:5]
	s_waitcnt vmcnt(0)

.LBB0_916:
	s_or_b64 exec, exec, s[2:3]
	s_mov_b64 s[2:3], exec
	v_mbcnt_lo_u32_b32 v1, s2, 0
	v_mbcnt_hi_u32_b32 v1, s3, v1
	s_mov_b32 s9, 0
	v_cmp_eq_u32_e32 vcc, 0, v1
	s_waitcnt vmcnt(0)
	buffer_inv sc1
	s_and_saveexec_b64 s[6:7], vcc
	s_cbranch_execz .LBB0_918
	s_add_i32 s8, s22, 0x900
	s_lshl_b64 s[8:9], s[8:9], 2
	s_add_u32 s8, s42, s8
	s_addc_u32 s9, s43, s9
	s_bcnt1_i32_b64 s2, s[2:3]
	v_mov_b32_e32 v1, 0
	v_mov_b32_e32 v2, s2
.LBB0_918:
	s_or_b64 exec, exec, s[6:7]
	s_waitcnt vmcnt(0)

.LBB0_1046:
	s_or_b64 exec, exec, s[4:5]
	s_mov_b64 s[4:5], exec
	v_mbcnt_lo_u32_b32 v1, s4, 0
	v_mbcnt_hi_u32_b32 v1, s5, v1
	s_mov_b32 s9, 0
	v_cmp_eq_u32_e32 vcc, 0, v1
	s_waitcnt vmcnt(0)
	buffer_inv sc1
	s_and_saveexec_b64 s[6:7], vcc
	s_cbranch_execz .LBB0_1048
	s_add_i32 s8, s22, 0x900
	s_lshl_b64 s[8:9], s[8:9], 2
	s_add_u32 s8, s42, s8
	s_addc_u32 s9, s43, s9
	s_bcnt1_i32_b64 s4, s[4:5]
	v_mov_b32_e32 v1, 0
	v_mov_b32_e32 v2, s4
.LBB0_1048:
	s_or_b64 exec, exec, s[6:7]
	s_waitcnt vmcnt(0)

.LBB0_1140:
	s_or_b64 exec, exec, s[4:5]
	s_mov_b64 s[4:5], exec
	v_mbcnt_lo_u32_b32 v1, s4, 0
	v_mbcnt_hi_u32_b32 v1, s5, v1
	s_mov_b32 s9, 0
	v_cmp_eq_u32_e32 vcc, 0, v1
	s_waitcnt vmcnt(0)
	buffer_inv sc1
	s_and_saveexec_b64 s[6:7], vcc
	s_cbranch_execz .LBB0_1142
	s_add_i32 s8, s22, 0x900
	s_lshl_b64 s[8:9], s[8:9], 2
	s_add_u32 s8, s42, s8
	s_addc_u32 s9, s43, s9
	s_bcnt1_i32_b64 s4, s[4:5]
	v_mov_b32_e32 v1, 0
	v_mov_b32_e32 v2, s4
.LBB0_1142:
	s_or_b64 exec, exec, s[6:7]
	s_waitcnt vmcnt(0)

.LBB0_1225:
	s_or_b64 exec, exec, s[4:5]
	s_mov_b64 s[4:5], exec
	v_mbcnt_lo_u32_b32 v1, s4, 0
	v_mbcnt_hi_u32_b32 v1, s5, v1
	s_mov_b32 s9, 0
	v_cmp_eq_u32_e32 vcc, 0, v1
	s_waitcnt vmcnt(0)
	buffer_inv sc1
	s_and_saveexec_b64 s[6:7], vcc
	s_cbranch_execz .LBB0_1227
	s_add_i32 s8, s22, 0x900
	s_lshl_b64 s[8:9], s[8:9], 2
	s_add_u32 s8, s42, s8
	s_addc_u32 s9, s43, s9
	s_bcnt1_i32_b64 s4, s[4:5]
	v_mov_b32_e32 v1, 0
	v_mov_b32_e32 v2, s4
.LBB0_1227:
	s_or_b64 exec, exec, s[6:7]
	s_waitcnt vmcnt(0)

.LBB0_1283:
	s_or_b64 exec, exec, s[2:3]
	s_mov_b64 s[2:3], exec
	v_mbcnt_lo_u32_b32 v1, s2, 0
	v_mbcnt_hi_u32_b32 v1, s3, v1
	s_mov_b32 s9, 0
	v_cmp_eq_u32_e32 vcc, 0, v1
	s_waitcnt vmcnt(0)
	buffer_inv sc1
	s_and_saveexec_b64 s[6:7], vcc
	s_cbranch_execz .LBB0_1285
	s_add_i32 s8, s22, 0x900
	s_lshl_b64 s[8:9], s[8:9], 2
	s_add_u32 s8, s42, s8
	s_addc_u32 s9, s43, s9
	s_bcnt1_i32_b64 s2, s[2:3]
	v_mov_b32_e32 v1, 0
	v_mov_b32_e32 v2, s2
.LBB0_1285:
	s_or_b64 exec, exec, s[6:7]
	s_waitcnt vmcnt(0)

.LBB0_1365:
	s_or_b64 exec, exec, s[2:3]
	s_mov_b64 s[2:3], exec
	v_mbcnt_lo_u32_b32 v1, s2, 0
	v_mbcnt_hi_u32_b32 v1, s3, v1
	s_mov_b32 s9, 0
	v_cmp_eq_u32_e32 vcc, 0, v1
	s_waitcnt vmcnt(0)
	buffer_inv sc1
	s_and_saveexec_b64 s[6:7], vcc
	s_cbranch_execz .LBB0_1367
	s_add_i32 s8, s22, 0x900
	s_lshl_b64 s[8:9], s[8:9], 2
	s_add_u32 s8, s42, s8
	s_addc_u32 s9, s43, s9
	s_bcnt1_i32_b64 s2, s[2:3]
	v_mov_b32_e32 v1, 0
	v_mov_b32_e32 v2, s2
.LBB0_1367:
	s_or_b64 exec, exec, s[6:7]
	s_waitcnt vmcnt(0)

.LBB0_1427:
	s_or_b64 exec, exec, s[4:5]
	s_mov_b64 s[4:5], exec
	v_mbcnt_lo_u32_b32 v1, s4, 0
	v_mbcnt_hi_u32_b32 v1, s5, v1
	s_mov_b32 s9, 0
	v_cmp_eq_u32_e32 vcc, 0, v1
	s_waitcnt vmcnt(0)
	buffer_inv sc1
	s_and_saveexec_b64 s[6:7], vcc
	s_cbranch_execz .LBB0_1429
	s_add_i32 s8, s22, 0x900
	s_lshl_b64 s[8:9], s[8:9], 2
	s_add_u32 s8, s42, s8
	s_addc_u32 s9, s43, s9
	s_bcnt1_i32_b64 s4, s[4:5]
	v_mov_b32_e32 v1, 0
	v_mov_b32_e32 v2, s4
.LBB0_1429:
	s_or_b64 exec, exec, s[6:7]
	s_waitcnt vmcnt(0)

.LBB0_1485:
	s_or_b64 exec, exec, s[4:5]
	s_mov_b64 s[4:5], exec
	v_mbcnt_lo_u32_b32 v1, s4, 0
	v_mbcnt_hi_u32_b32 v1, s5, v1
	s_mov_b32 s9, 0
	v_cmp_eq_u32_e32 vcc, 0, v1
	s_waitcnt vmcnt(0)
	buffer_inv sc1
	s_and_saveexec_b64 s[6:7], vcc
	s_cbranch_execz .LBB0_1487
	s_add_i32 s8, s22, 0x900
	s_lshl_b64 s[8:9], s[8:9], 2
	s_add_u32 s8, s42, s8
	s_addc_u32 s9, s43, s9
	s_bcnt1_i32_b64 s4, s[4:5]
	v_mov_b32_e32 v1, 0
	v_mov_b32_e32 v2, s4
.LBB0_1487:
	s_or_b64 exec, exec, s[6:7]
	s_waitcnt vmcnt(0)

.LBB0_1557:
	s_or_b64 exec, exec, s[2:3]
	s_mov_b64 s[2:3], exec
	v_mbcnt_lo_u32_b32 v1, s2, 0
	v_mbcnt_hi_u32_b32 v1, s3, v1
	s_mov_b32 s9, 0
	v_cmp_eq_u32_e32 vcc, 0, v1
	s_waitcnt vmcnt(0)
	buffer_inv sc1
	s_and_saveexec_b64 s[4:5], vcc
	s_cbranch_execz .LBB0_1559
	s_add_i32 s8, s22, 0x900
	s_lshl_b64 s[8:9], s[8:9], 2
	s_add_u32 s8, s42, s8
	s_addc_u32 s9, s43, s9
	s_bcnt1_i32_b64 s2, s[2:3]
	v_mov_b32_e32 v1, 0
	v_mov_b32_e32 v2, s2
.LBB0_1559:
	s_or_b64 exec, exec, s[4:5]
	s_waitcnt vmcnt(0)

.LBB0_1586:
	s_or_b64 exec, exec, s[4:5]
	v_cvt_f32_u32_e32 v4, v2
	s_waitcnt vmcnt(0)
	v_readfirstlane_b32 s2, v3
	v_sub_u32_e32 v3, 0, v2
	v_rcp_iflag_f32_e32 v4, v4
	v_add_u32_e32 v5, s2, v1
	v_mul_f32_e32 v4, 0x4f7ffffe, v4
	v_cvt_u32_f32_e32 v4, v4
	v_mul_lo_u32 v1, v3, v4
	v_mul_hi_u32 v1, v4, v1
	v_add_u32_e32 v1, v4, v1
	v_mul_hi_u32 v1, v5, v1
	v_mul_lo_u32 v3, v1, v2
	v_sub_u32_e32 v3, v5, v3
	v_add_u32_e32 v4, 1, v1
	v_cmp_ge_u32_e32 vcc, v3, v2
	s_nop 1
	v_cndmask_b32_e32 v1, v1, v4, vcc
	v_sub_u32_e32 v4, v3, v2
	v_cndmask_b32_e32 v3, v3, v4, vcc
	v_add_u32_e32 v4, 1, v1
	v_cmp_ge_u32_e32 vcc, v3, v2
	v_add_u32_e32 v3, 1, v5
	s_nop 0
	v_cndmask_b32_e32 v1, v1, v4, vcc
	v_mul_lo_u32 v4, v2, v1
	v_add_u32_e32 v2, v4, v2
	v_cmp_ne_u32_e32 vcc, v3, v2
	s_and_saveexec_b64 s[2:3], vcc
	s_xor_b64 s[2:3], exec, s[2:3]
	s_cbranch_execz .LBB0_1600
	s_movk_i32 s4, 0xd40
	s_mov_b32 s5, 0
	s_lshl_b64 s[4:5], s[4:5], 2
	s_add_u32 s6, s42, s4
	s_addc_u32 s7, s43, s5
	s_waitcnt lgkmcnt(0)
	v_mov_b32_e32 v0, 0
	global_load_dword v2, v0, s[6:7] sc1
	s_waitcnt vmcnt(0)
	v_cmp_eq_u32_e32 vcc, v2, v1
	s_and_saveexec_b64 s[4:5], vcc
	s_cbranch_execz .LBB0_1599
	s_mov_b32 s18, 1
	s_mov_b64 s[8:9], 0
	s_branch .LBB0_1590

.LBB0_1617:
	s_or_b64 exec, exec, s[2:3]
	s_mov_b64 s[2:3], exec
	v_mbcnt_lo_u32_b32 v0, s2, 0
	v_mbcnt_hi_u32_b32 v0, s3, v0
	s_mov_b32 s7, 0
	v_cmp_eq_u32_e32 vcc, 0, v0
	s_waitcnt vmcnt(0)
	buffer_inv sc1
	s_and_saveexec_b64 s[4:5], vcc
	s_cbranch_execz .LBB0_1619
	s_add_i32 s6, s20, 0x900
	s_lshl_b64 s[6:7], s[6:7], 2
	s_add_u32 s6, s42, s6
	s_addc_u32 s7, s43, s7
	s_bcnt1_i32_b64 s2, s[2:3]
	v_mov_b32_e32 v0, 0
	v_mov_b32_e32 v1, s2
.LBB0_1619:
	s_or_b64 exec, exec, s[4:5]
	s_waitcnt vmcnt(0)
